# attention: v_pk_add_f32 row-sum ops split into scalar v_add_f32 pairs (bit-identical)
# baseline (speedup 1.0000x reference)
; template <int DQK, bool MIXA, bool PIPE>
; DI void attn_item(const Params& P, int layer, char* smem, int b, int h, int qt) {
;     ...
;       for (int s = 0; s < NS; ++s) sacc[0] = __builtin_amdgcn_mfma_f32_32x32x16_bf16(kf[0][s], qf[s], sacc[0], 0, 0, 0);
;       bf16x8 vf[2][2][2];
; #pragma unroll
;       for (int d = 0; d < 2; ++d)
; #pragma unroll
;         for (int kb = 0; kb < 2; ++kb)
; #pragma unroll
;           for (int s2 = 0; s2 < 2; ++s2)
;             vf[d][kb][s2] = *(const bf16x8*)(Vs + (d * 32 + l31) * 128 + (((4 * kb + 2 * s2 + H) ^ swv) << 4));
;       __builtin_amdgcn_sched_barrier(0);
;       const bool near = MIXA && (kc >= cw - 2);
;       f32x2 ls2 = {0.f, 0.f};
;       const f32x2 sl2v = {sl2, sl2}, mfixv = {mfix, mfix};
;       unsigned pkw[2][2][4];
;       unsigned mrot[2];
; #pragma unroll
;       for (int kb = 0; kb < 2; ++kb) mrot[kb] = MIXA ? ((mw[kb] >> (8 * H)) << 8) : 0u;
;       auto chunk = [&](int kb, int c) __attribute__((always_inline)) {
;         const int s2 = 1 - (c >> 2), e = 3 - (c & 3);
;         const int r0 = 8 * s2 + 2 * e;
;         if (MIXA && c == 4) mrot[kb] <<= 8;
;         f32x2 xv2 = {sacc[kb][r0], sacc[kb][r0 + 1]};
;         xv2 = xv2 * sl2v - mfixv;
;         if (MIXA) {
;           if (near) {
;             const int kl = 16 * (r0 >> 3) + 8 * H + (r0 & 7);
;             const int rel = kc * 64 + 32 * kb + kl - qpos;
;             xv2.x += biasT[rel + 192];
;             xv2.y += biasT[rel + 193];
;           }
;         }
;         f32x2 p2 = {__builtin_amdgcn_exp2f(xv2.x), __builtin_amdgcn_exp2f(xv2.y)};
;         if (MIXA) {
;           float px = p2.x, py = p2.y;
;           asm volatile("v_add_co_u32 %0, vcc, %0, %0\n\tv_cndmask_b32 %1, 0, %1, vcc" : "+v"(mrot[kb]), "+v"(py) : : "vcc");
;           asm volatile("v_add_co_u32 %0, vcc, %0, %0\n\tv_cndmask_b32 %1, 0, %1, vcc" : "+v"(mrot[kb]), "+v"(px) : : "vcc");
;           p2.x = px; p2.y = py;
;         }
;         ls2 += p2;
;         pkw[kb][s2][e] = pk2(p2.x, p2.y);
;       };
;       {
;         int c0 = 0;
; #pragma unroll
;         for (int s = 0; s < NS; ++s) {
;           sacc[1] = __builtin_amdgcn_mfma_f32_32x32x16_bf16(kf[1][s], qf[s], sacc[1], 0, 0, 0);
;           const int cend = (8 * (s + 1)) / NS;
; #pragma unroll
;           for (int c = 0; c < 8; ++c) if (c >= c0 && c < cend) chunk(0, c);
;           c0 = cend;
.LBB0_87:
	s_add_i32 s20, s22, 1
	s_bitcmp1_b32 s20, 0
	s_cselect_b32 s21, 0x5000, 0
	s_add_u32 m0, s21, s32
	s_add_u32 s18, s21, s73
	global_load_lds_dwordx4 v120, s[36:37]
	s_add_u32 m0, m0, 0x400
	s_nop 0
	global_load_lds_dwordx4 v122, s[36:37]
	s_add_u32 m0, m0, 0x400
	s_nop 0
	global_load_lds_dwordx4 v124, s[36:37]
	s_add_u32 m0, s18, 0x3000
	v_cmp_le_i32_e32 vcc, s22, v127
	global_load_lds_dwordx4 v116, s[38:39]
	s_add_u32 m0, s18, 0x3400
	s_nop 0
	global_load_lds_dwordx4 v118, s[38:39]
	s_and_saveexec_b64 s[18:19], vcc
	s_cbranch_execz .LBB0_86
	s_bitcmp1_b32 s22, 0
	s_cselect_b32 s22, 0x5000, 0
	v_add_u32_e32 v32, s22, v141
	v_add_u32_e32 v36, v32, v140
	v_add_u32_e32 v44, v32, v142
	v_add_u32_e32 v48, v32, v143
	v_add_u32_e32 v49, v32, v144
	v_add_u32_e32 v50, v32, v145
	v_add_u32_e32 v51, v32, v146
	ds_read_b128 v[32:35], v36
	ds_read_b128 v[36:39], v36 offset:6144
	ds_read_b128 v[40:43], v44
	ds_read_b128 v[148:151], v44 offset:6144
	ds_read_b128 v[44:47], v48
	ds_read_b128 v[152:155], v48 offset:6144
	ds_read_b128 v[88:91], v49
	ds_read_b128 v[156:159], v49 offset:6144
	ds_read_b128 v[92:95], v50
	ds_read_b128 v[208:211], v50 offset:6144
	ds_read_b128 v[96:99], v51
	ds_read_b128 v[212:215], v51 offset:6144
	s_waitcnt lgkmcnt(0)
	v_mfma_f32_32x32x16_bf16 v[48:63], v[32:35], v[84:87], v[228:243]
	v_or_b32_e32 v32, s22, v129
	v_add_u32_e32 v33, v32, v134
	v_add_u32_e32 v34, v32, v133
	v_add_u32_e32 v35, v32, v130
	v_add_u32_e32 v32, v32, v131
	ds_read_b128 v[216:219], v33 offset:12288
	ds_read_b128 v[108:111], v34 offset:12288
	v_mfma_f32_32x32x16_bf16 v[48:63], v[40:43], v[80:83], v[48:63]
	v_mfma_f32_32x32x16_bf16 v[48:63], v[44:47], v[76:79], v[48:63]
	v_mfma_f32_32x32x16_bf16 v[48:63], v[88:91], v[72:75], v[48:63]
	ds_read_b128 v[88:91], v35 offset:12288
	v_mfma_f32_32x32x16_bf16 v[48:63], v[92:95], v[68:71], v[48:63]
	v_mfma_f32_32x32x16_bf16 v[48:63], v[96:99], v[64:67], v[48:63]
	ds_read_b128 v[92:95], v32 offset:12288
	ds_read_b128 v[220:223], v33 offset:16384
	ds_read_b128 v[104:107], v34 offset:16384
	ds_read_b128 v[100:103], v35 offset:16384
	ds_read_b128 v[96:99], v32 offset:16384
	s_nop 6
	s_nop 0
	v_exp_f32_e32 v32, v62
	v_exp_f32_e32 v33, v63
	s_nop 0
	v_add_f32_e32 v224, 0, v32
	v_add_f32_e32 v225, 0, v33
	v_cvt_pk_bf16_f32 v63, v32, v33
	v_mfma_f32_32x32x16_bf16 v[32:47], v[36:39], v[84:87], v[228:243]
	v_mfma_f32_32x32x16_bf16 v[32:47], v[148:151], v[80:83], v[32:47]
	v_exp_f32_e32 v60, v60
	v_exp_f32_e32 v61, v61
	s_nop 0
	v_add_f32_e32 v224, v60, v224
	v_add_f32_e32 v225, v61, v225
	v_cvt_pk_bf16_f32 v62, v60, v61
	v_exp_f32_e32 v58, v58
	v_exp_f32_e32 v59, v59
	v_exp_f32_e32 v56, v56
	v_exp_f32_e32 v57, v57
	v_mfma_f32_32x32x16_bf16 v[32:47], v[152:155], v[76:79], v[32:47]
	v_add_f32_e64 v148, v58, v224
	v_add_f32_e64 v149, v59, v225
	v_cvt_pk_bf16_f32 v61, v58, v59
	v_add_f32_e64 v58, v56, v148
	v_add_f32_e64 v59, v57, v149
	v_cvt_pk_bf16_f32 v60, v56, v57
	v_mfma_f32_32x32x16_bf16 v[32:47], v[156:159], v[72:75], v[32:47]
	v_exp_f32_e32 v54, v54
	v_exp_f32_e32 v55, v55
	s_nop 0
	v_add_f32_e32 v56, v54, v58
	v_add_f32_e32 v57, v55, v59
	v_cvt_pk_bf16_f32 v55, v54, v55
	v_mfma_f32_32x32x16_bf16 v[32:47], v[208:211], v[68:71], v[32:47]
	v_exp_f32_e32 v52, v52
	v_exp_f32_e32 v53, v53
	s_nop 0
	v_add_f32_e32 v56, v52, v56
	v_add_f32_e32 v57, v53, v57
	v_cvt_pk_bf16_f32 v54, v52, v53
	v_exp_f32_e32 v50, v50
	v_exp_f32_e32 v51, v51
	v_exp_f32_e32 v48, v48
	v_exp_f32_e32 v49, v49
	v_mfma_f32_32x32x16_bf16 v[32:47], v[212:215], v[64:67], v[32:47]
	v_add_f32_e64 v56, v50, v56
	v_add_f32_e64 v57, v51, v57
	v_cvt_pk_bf16_f32 v53, v50, v51
	v_cvt_pk_bf16_f32 v52, v48, v49
	v_add_f32_e64 v48, v48, v56
	v_add_f32_e64 v49, v49, v57
	s_waitcnt lgkmcnt(0)
	v_mfma_f32_32x32x16_bf16 v[0:15], v[216:219], v[52:55], v[0:15]
	s_nop 3
	v_exp_f32_e32 v46, v46
	v_exp_f32_e32 v47, v47
	v_exp_f32_e32 v44, v44
	v_exp_f32_e32 v45, v45
	v_add_f32_e32 v48, v48, v46
	v_add_f32_e32 v49, v49, v47
	v_cvt_pk_bf16_f32 v47, v46, v47
	v_add_f32_e32 v48, v44, v48
	v_add_f32_e32 v49, v45, v49
	v_cvt_pk_bf16_f32 v46, v44, v45
	v_mfma_f32_32x32x16_bf16 v[16:31], v[220:223], v[52:55], v[16:31]
	v_exp_f32_e32 v42, v42
	v_exp_f32_e32 v43, v43
	v_exp_f32_e32 v40, v40
	v_exp_f32_e32 v41, v41
	v_add_f32_e32 v48, v42, v48
	v_add_f32_e32 v49, v43, v49
	v_cvt_pk_bf16_f32 v45, v42, v43
	v_add_f32_e32 v42, v40, v48
	v_add_f32_e32 v43, v41, v49
	v_cvt_pk_bf16_f32 v44, v40, v41
	v_mfma_f32_32x32x16_bf16 v[0:15], v[108:111], v[60:63], v[0:15]
	v_exp_f32_e32 v38, v38
	v_exp_f32_e32 v39, v39
	v_exp_f32_e32 v36, v36
	v_exp_f32_e32 v37, v37
	v_add_f32_e32 v40, v38, v42
	v_add_f32_e32 v41, v39, v43
	v_cvt_pk_bf16_f32 v39, v38, v39
	v_add_f32_e32 v40, v36, v40
	v_add_f32_e32 v41, v37, v41
	v_cvt_pk_bf16_f32 v38, v36, v37
	v_mfma_f32_32x32x16_bf16 v[16:31], v[104:107], v[60:63], v[16:31]
	v_exp_f32_e32 v34, v34
	v_exp_f32_e32 v35, v35
	v_exp_f32_e32 v32, v32
	v_exp_f32_e32 v33, v33
	v_cvt_pk_bf16_f32 v37, v34, v35
	v_cvt_pk_bf16_f32 v36, v32, v33
	s_nop 1
	v_mfma_f32_32x32x16_bf16 v[0:15], v[88:91], v[36:39], v[0:15]
	v_add_f32_e64 v34, v34, v40
	v_add_f32_e64 v35, v35, v41
	v_add_f32_e64 v32, v32, v34
	v_add_f32_e64 v33, v33, v35
	v_add_f32_e32 v32, v32, v33
	v_add_f32_e32 v126, v126, v32
	v_mfma_f32_32x32x16_bf16 v[16:31], v[100:103], v[36:39], v[16:31]
	v_mfma_f32_32x32x16_bf16 v[0:15], v[92:95], v[44:47], v[0:15]
	v_mfma_f32_32x32x16_bf16 v[16:31], v[96:99], v[44:47], v[16:31]
	s_branch .LBB0_86
; template <int DQK, bool MIXA, bool PIPE>
; DI void attn_item(const Params& P, int layer, char* smem, int b, int h, int qt) {
;     ...
;       for (int s = 0; s < NS; ++s) sacc[0] = __builtin_amdgcn_mfma_f32_32x32x16_bf16(kf[0][s], qf[s], sacc[0], 0, 0, 0);
;       bf16x8 vf[2][2][2];
; #pragma unroll
;       for (int d = 0; d < 2; ++d)
; #pragma unroll
;         for (int kb = 0; kb < 2; ++kb)
; #pragma unroll
;           for (int s2 = 0; s2 < 2; ++s2)
;             vf[d][kb][s2] = *(const bf16x8*)(Vs + (d * 32 + l31) * 128 + (((4 * kb + 2 * s2 + H) ^ swv) << 4));
;       __builtin_amdgcn_sched_barrier(0);
;       const bool near = MIXA && (kc >= cw - 2);
;       f32x2 ls2 = {0.f, 0.f};
;       const f32x2 sl2v = {sl2, sl2}, mfixv = {mfix, mfix};
;       unsigned pkw[2][2][4];
;       unsigned mrot[2];
; #pragma unroll
;       for (int kb = 0; kb < 2; ++kb) mrot[kb] = MIXA ? ((mw[kb] >> (8 * H)) << 8) : 0u;
;       auto chunk = [&](int kb, int c) __attribute__((always_inline)) {
;         const int s2 = 1 - (c >> 2), e = 3 - (c & 3);
;         const int r0 = 8 * s2 + 2 * e;
;         if (MIXA && c == 4) mrot[kb] <<= 8;
;         f32x2 xv2 = {sacc[kb][r0], sacc[kb][r0 + 1]};
;         xv2 = xv2 * sl2v - mfixv;
;         if (MIXA) {
;           if (near) {
;             const int kl = 16 * (r0 >> 3) + 8 * H + (r0 & 7);
;             const int rel = kc * 64 + 32 * kb + kl - qpos;
;             xv2.x += biasT[rel + 192];
;             xv2.y += biasT[rel + 193];
;           }
;         }
;         f32x2 p2 = {__builtin_amdgcn_exp2f(xv2.x), __builtin_amdgcn_exp2f(xv2.y)};
;         if (MIXA) {
;           float px = p2.x, py = p2.y;
;           asm volatile("v_add_co_u32 %0, vcc, %0, %0\n\tv_cndmask_b32 %1, 0, %1, vcc" : "+v"(mrot[kb]), "+v"(py) : : "vcc");
;           asm volatile("v_add_co_u32 %0, vcc, %0, %0\n\tv_cndmask_b32 %1, 0, %1, vcc" : "+v"(mrot[kb]), "+v"(px) : : "vcc");
;           p2.x = px; p2.y = py;
;         }
;         ls2 += p2;
;         pkw[kb][s2][e] = pk2(p2.x, p2.y);
;       };
;       {
;         int c0 = 0;
; #pragma unroll
;         for (int s = 0; s < NS; ++s) {
;           sacc[1] = __builtin_amdgcn_mfma_f32_32x32x16_bf16(kf[1][s], qf[s], sacc[1], 0, 0, 0);
;           const int cend = (8 * (s + 1)) / NS;
; #pragma unroll
;           for (int c = 0; c < 8; ++c) if (c >= c0 && c < cend) chunk(0, c);
;           c0 = cend;
.LBB0_89:
	s_or_b64 exec, exec, s[44:45]
	v_cmp_lt_i32_e32 vcc, v128, v127
	s_and_saveexec_b64 s[18:19], vcc
	s_cbranch_execz .LBB0_91
	v_add_u32_e32 v33, v32, v141
	v_add_u32_e32 v38, v33, v140
	v_add_u32_e32 v46, v33, v142
	v_add_u32_e32 v47, v33, v143
	v_add_u32_e32 v48, v33, v144
	v_add_u32_e32 v49, v33, v145
	v_add_u32_e32 v33, v33, v146
	ds_read_b128 v[34:37], v38
	ds_read_b128 v[38:41], v38 offset:6144
	ds_read_b128 v[42:45], v46
	ds_read_b128 v[116:119], v46 offset:6144
	ds_read_b128 v[88:91], v47
	ds_read_b128 v[120:123], v47 offset:6144
	ds_read_b128 v[92:95], v48
	ds_read_b128 v[140:143], v48 offset:6144
	ds_read_b128 v[96:99], v49
	ds_read_b128 v[144:147], v49 offset:6144
	ds_read_b128 v[100:103], v33
	ds_read_b128 v[148:151], v33 offset:6144
	s_waitcnt lgkmcnt(11)
	v_mfma_f32_32x32x16_bf16 v[48:63], v[34:37], v[84:87], v[228:243]
	v_add_u32_e32 v32, v32, v129
	v_add_u32_e32 v33, v32, v134
	v_add_u32_e32 v34, v32, v133
	v_add_u32_e32 v35, v32, v130
	v_add_u32_e32 v32, v32, v131
	ds_read_b128 v[152:155], v33 offset:12288
	ds_read_b128 v[108:111], v34 offset:12288
	s_waitcnt lgkmcnt(11)
	v_mfma_f32_32x32x16_bf16 v[48:63], v[42:45], v[80:83], v[48:63]
	s_waitcnt lgkmcnt(9)
	v_mfma_f32_32x32x16_bf16 v[48:63], v[88:91], v[76:79], v[48:63]
	ds_read_b128 v[88:91], v35 offset:12288
	s_waitcnt lgkmcnt(8)
	v_mfma_f32_32x32x16_bf16 v[48:63], v[92:95], v[72:75], v[48:63]
	s_waitcnt lgkmcnt(6)
	v_mfma_f32_32x32x16_bf16 v[48:63], v[96:99], v[68:71], v[48:63]
	s_waitcnt lgkmcnt(4)
	v_mfma_f32_32x32x16_bf16 v[48:63], v[100:103], v[64:67], v[48:63]
	ds_read_b128 v[92:95], v32 offset:12288
	ds_read_b128 v[128:131], v33 offset:16384
	ds_read_b128 v[104:107], v34 offset:16384
	ds_read_b128 v[100:103], v35 offset:16384
	ds_read_b128 v[96:99], v32 offset:16384
	s_nop 6
	s_nop 0
	v_exp_f32_e32 v32, v62
	v_exp_f32_e32 v33, v63
	s_nop 0
	v_add_f32_e32 v124, 0, v32
	v_add_f32_e32 v125, 0, v33
	v_cvt_pk_bf16_f32 v63, v32, v33
	v_mfma_f32_32x32x16_bf16 v[32:47], v[38:41], v[84:87], v[228:243]
	v_mfma_f32_32x32x16_bf16 v[32:47], v[116:119], v[80:83], v[32:47]
	v_exp_f32_e32 v60, v60
	v_exp_f32_e32 v61, v61
	s_nop 0
	v_add_f32_e32 v84, v60, v124
	v_add_f32_e32 v85, v61, v125
	v_cvt_pk_bf16_f32 v62, v60, v61
	v_exp_f32_e32 v58, v58
	v_exp_f32_e32 v59, v59
	v_exp_f32_e32 v56, v56
	v_exp_f32_e32 v57, v57
	v_mfma_f32_32x32x16_bf16 v[32:47], v[120:123], v[76:79], v[32:47]
	v_add_f32_e64 v80, v58, v84
	v_add_f32_e64 v81, v59, v85
	v_cvt_pk_bf16_f32 v61, v58, v59
	v_add_f32_e64 v58, v56, v80
	v_add_f32_e64 v59, v57, v81
	v_cvt_pk_bf16_f32 v60, v56, v57
	v_mfma_f32_32x32x16_bf16 v[32:47], v[140:143], v[72:75], v[32:47]
	v_exp_f32_e32 v54, v54
	v_exp_f32_e32 v55, v55
	s_nop 0
	v_add_f32_e32 v56, v54, v58
	v_add_f32_e32 v57, v55, v59
	v_cvt_pk_bf16_f32 v55, v54, v55
	v_mfma_f32_32x32x16_bf16 v[32:47], v[144:147], v[68:71], v[32:47]
	v_exp_f32_e32 v52, v52
	v_exp_f32_e32 v53, v53
	s_nop 0
	v_add_f32_e32 v56, v52, v56
	v_add_f32_e32 v57, v53, v57
	v_cvt_pk_bf16_f32 v54, v52, v53
	v_exp_f32_e32 v50, v50
	v_exp_f32_e32 v51, v51
	v_exp_f32_e32 v48, v48
	v_exp_f32_e32 v49, v49
	s_waitcnt lgkmcnt(8)
	v_mfma_f32_32x32x16_bf16 v[32:47], v[148:151], v[64:67], v[32:47]
	v_add_f32_e64 v56, v50, v56
	v_add_f32_e64 v57, v51, v57
	v_cvt_pk_bf16_f32 v53, v50, v51
	v_cvt_pk_bf16_f32 v52, v48, v49
	v_add_f32_e64 v48, v48, v56
	v_add_f32_e64 v49, v49, v57
	s_waitcnt lgkmcnt(7)
	v_mfma_f32_32x32x16_bf16 v[0:15], v[152:155], v[52:55], v[0:15]
	s_nop 3
	v_exp_f32_e32 v46, v46
	v_exp_f32_e32 v47, v47
	v_exp_f32_e32 v44, v44
	v_exp_f32_e32 v45, v45
	v_add_f32_e32 v48, v48, v46
	v_add_f32_e32 v49, v49, v47
	v_cvt_pk_bf16_f32 v47, v46, v47
	v_add_f32_e32 v48, v44, v48
	v_add_f32_e32 v49, v45, v49
	v_cvt_pk_bf16_f32 v46, v44, v45
	s_waitcnt lgkmcnt(3)
	v_mfma_f32_32x32x16_bf16 v[16:31], v[128:131], v[52:55], v[16:31]
	v_exp_f32_e32 v42, v42
	v_exp_f32_e32 v43, v43
	v_exp_f32_e32 v40, v40
	v_exp_f32_e32 v41, v41
	v_add_f32_e32 v48, v42, v48
	v_add_f32_e32 v49, v43, v49
	v_cvt_pk_bf16_f32 v45, v42, v43
	v_add_f32_e32 v42, v40, v48
	v_add_f32_e32 v43, v41, v49
	v_cvt_pk_bf16_f32 v44, v40, v41
	v_mfma_f32_32x32x16_bf16 v[0:15], v[108:111], v[60:63], v[0:15]
	v_exp_f32_e32 v38, v38
	v_exp_f32_e32 v39, v39
	v_exp_f32_e32 v36, v36
	v_exp_f32_e32 v37, v37
	v_add_f32_e32 v40, v38, v42
	v_add_f32_e32 v41, v39, v43
	v_cvt_pk_bf16_f32 v39, v38, v39
	v_add_f32_e32 v40, v36, v40
	v_add_f32_e32 v41, v37, v41
	v_cvt_pk_bf16_f32 v38, v36, v37
	s_waitcnt lgkmcnt(2)
	v_mfma_f32_32x32x16_bf16 v[16:31], v[104:107], v[60:63], v[16:31]
	v_exp_f32_e32 v34, v34
	v_exp_f32_e32 v35, v35
	v_exp_f32_e32 v32, v32
	v_exp_f32_e32 v33, v33
	v_cvt_pk_bf16_f32 v37, v34, v35
	v_cvt_pk_bf16_f32 v36, v32, v33
	s_nop 1
	v_mfma_f32_32x32x16_bf16 v[0:15], v[88:91], v[36:39], v[0:15]
	v_add_f32_e64 v34, v34, v40
	v_add_f32_e64 v35, v35, v41
	v_add_f32_e64 v32, v32, v34
	v_add_f32_e64 v33, v33, v35
	v_add_f32_e32 v32, v32, v33
	v_add_f32_e32 v126, v126, v32
	s_waitcnt lgkmcnt(1)
	v_mfma_f32_32x32x16_bf16 v[16:31], v[100:103], v[36:39], v[16:31]
	v_mfma_f32_32x32x16_bf16 v[0:15], v[92:95], v[44:47], v[0:15]
	s_waitcnt lgkmcnt(0)
	v_mfma_f32_32x32x16_bf16 v[16:31], v[96:99], v[44:47], v[16:31]

; DI unsigned pk2(float a, float b) { f32x2 v = {a, b}; return __builtin_bit_cast(unsigned, __builtin_convertvector(v, bf16x2)); }
; template <int DQK, bool MIXA, bool PIPE>
; DI void attn_item(const Params& P, int layer, char* smem, int b, int h, int qt) {
;     ...
;         f32x2 p2 = {__builtin_amdgcn_exp2f(xv2.x), __builtin_amdgcn_exp2f(xv2.y)};
;         if (MIXA) {
;           float px = p2.x, py = p2.y;
;           asm volatile("v_add_co_u32 %0, vcc, %0, %0\n\tv_cndmask_b32 %1, 0, %1, vcc" : "+v"(mrot[kb]), "+v"(py) : : "vcc");
;           asm volatile("v_add_co_u32 %0, vcc, %0, %0\n\tv_cndmask_b32 %1, 0, %1, vcc" : "+v"(mrot[kb]), "+v"(px) : : "vcc");
;           p2.x = px; p2.y = py;
;         }
;         ls2 += p2;
;         pkw[kb][s2][e] = pk2(p2.x, p2.y);
;       };
;       {
;         int c0 = 0;
; #pragma unroll
;         for (int s = 0; s < NS; ++s) {
;           sacc[1] = __builtin_amdgcn_mfma_f32_32x32x16_bf16(kf[1][s], qf[s], sacc[1], 0, 0, 0);
;           const int cend = (8 * (s + 1)) / NS;
; #pragma unroll
;           for (int c = 0; c < 8; ++c) if (c >= c0 && c < cend) chunk(0, c);
;           c0 = cend;
;           __builtin_amdgcn_sched_barrier(0);
;         }
;       }
;       bf16x8 pf0[2], pf1[2];
; #pragma unroll
;       for (int s2 = 0; s2 < 2; ++s2) { u32x4 t = {pkw[0][s2][0], pkw[0][s2][1], pkw[0][s2][2], pkw[0][s2][3]}; pf0[s2] = __builtin_bit_cast(bf16x8, t); }
; #pragma unroll
;       for (int j = 0; j < 4; ++j) {
;         const int s2 = j >> 1, d = j & 1;
;         o[d] = __builtin_amdgcn_mfma_f32_32x32x16_bf16(vf[d][0][s2], pf0[s2], o[d], 0, 0, 0);
;         chunk(1, 2 * j); chunk(1, 2 * j + 1);
;         __builtin_amdgcn_sched_barrier(0);
;       }
; #pragma unroll
;       for (int s2 = 0; s2 < 2; ++s2) { u32x4 t = {pkw[1][s2][0], pkw[1][s2][1], pkw[1][s2][2], pkw[1][s2][3]}; pf1[s2] = __builtin_bit_cast(bf16x8, t); }
; #pragma unroll
;       for (int j = 0; j < 4; ++j) {
;         const int s2 = j >> 1, d = j & 1;
;         o[d] = __builtin_amdgcn_mfma_f32_32x32x16_bf16(vf[d][1][s2], pf1[s2], o[d], 0, 0, 0);
;       }
;       l += ls2.x + ls2.y;
.LBB0_108:
	v_add_f32_e32 v40, 0, v62
	v_add_f32_e32 v41, 0, v63
	v_exp_f32_e32 v33, v33
	v_add_f32_e32 v40, v40, v60
	v_add_f32_e32 v41, v41, v61
	v_exp_f32_e32 v32, v32
	v_add_f32_e32 v40, v40, v58
	v_add_f32_e32 v41, v41, v59
	v_add_co_u32 v100, vcc, v100, v100
	v_cndmask_b32 v33, 0, v33, vcc
	s_nop 0
	v_add_f32_e32 v40, v40, v56
	v_add_f32_e32 v41, v41, v57
	v_add_co_u32 v100, vcc, v100, v100
	v_cndmask_b32 v32, 0, v32, vcc
	s_nop 0
	v_add_f32_e32 v40, v40, v54
	v_add_f32_e32 v41, v41, v55
	s_nop 0
	v_add_f32_e32 v40, v40, v52
	v_add_f32_e32 v41, v41, v53
	s_nop 0
	v_add_f32_e32 v40, v40, v116
	v_add_f32_e32 v41, v41, v117
	s_nop 0
	v_add_f32_e32 v40, v40, v118
	v_add_f32_e32 v41, v41, v119
	s_nop 0
	v_add_f32_e32 v40, v40, v46
	v_add_f32_e32 v41, v41, v47
	s_nop 0
	v_add_f32_e32 v40, v40, v44
	v_add_f32_e32 v41, v41, v45
	s_nop 0
	v_add_f32_e32 v40, v40, v48
	v_add_f32_e32 v41, v41, v49
	s_nop 0
	v_add_f32_e32 v40, v40, v50
	v_add_f32_e32 v41, v41, v51
	s_nop 0
	v_add_f32_e32 v40, v40, v38
	v_add_f32_e32 v41, v41, v39
	s_nop 0
	v_add_f32_e32 v40, v40, v36
	v_add_f32_e32 v41, v41, v37
	v_cvt_pk_bf16_f32 v36, v36, v37
	v_add_f32_e32 v42, v40, v34
	v_add_f32_e32 v43, v41, v35
	v_cvt_pk_bf16_f32 v35, v34, v35
	v_cvt_pk_bf16_f32 v37, v38, v39
	v_cvt_pk_bf16_f32 v38, v50, v51
	v_cvt_pk_bf16_f32 v39, v48, v49
	v_cvt_pk_bf16_f32 v40, v44, v45
	v_cvt_pk_bf16_f32 v41, v46, v47
	v_cvt_pk_bf16_f32 v34, v32, v33
	s_nop 1
	v_mfma_f32_32x32x16_bf16 v[0:15], v[80:83], v[34:37], v[0:15]
	v_add_f32_e64 v32, v42, v32
	v_add_f32_e64 v33, v43, v33
	v_add_f32_e32 v32, v32, v33
	v_add_f32_e32 v125, v125, v32
	v_mfma_f32_32x32x16_bf16 v[16:31], v[92:95], v[34:37], v[16:31]
	v_mfma_f32_32x32x16_bf16 v[0:15], v[84:87], v[38:41], v[0:15]
	v_mfma_f32_32x32x16_bf16 v[16:31], v[88:91], v[38:41], v[16:31]
